# v69 + write-through and non-temporal (sc1 nt) on the gate / t2 output stores of the scan-independent GEMM fast paths
# speedup vs baseline: 1.0082x; 1.0057x over previous
.Lsh_k01:
	s_cmp_eq_u32 s63, 0
	s_cselect_b32 s5, s43, s45
	s_cselect_b32 s4, s42, s44
	v_mov_b32_e32 v156, v136
	v_add_u32_e32 v157, 0x8000, v136
	v_add_u32_e32 v158, 0x10000, v136
	v_add_u32_e32 v159, 0x18000, v136
	v_add_u32_e32 v160, 0x40000, v136
	v_add_u32_e32 v161, 0x48000, v136
	v_add_u32_e32 v162, 0x50000, v136
	v_add_u32_e32 v163, 0x58000, v136
	v_mul_f32_e32 v124, 0xbfb8aa3b, v124
	v_mul_f32_e32 v120, 0xbfb8aa3b, v120
	v_mul_f32_e32 v125, 0xbfb8aa3b, v125
	v_mul_f32_e32 v121, 0xbfb8aa3b, v121
	v_mul_f32_e32 v126, 0xbfb8aa3b, v126
	v_mul_f32_e32 v122, 0xbfb8aa3b, v122
	v_mul_f32_e32 v123, 0xbfb8aa3b, v123
	v_mul_f32_e32 v127, 0xbfb8aa3b, v127
	v_exp_f32_e32 v124, v124
	v_exp_f32_e32 v120, v120
	v_exp_f32_e32 v125, v125
	v_exp_f32_e32 v121, v121
	v_exp_f32_e32 v126, v126
	v_exp_f32_e32 v122, v122
	v_exp_f32_e32 v123, v123
	v_exp_f32_e32 v127, v127
	v_add_f32_e32 v124, 1.0, v124
	v_add_f32_e32 v120, 1.0, v120
	v_add_f32_e32 v125, 1.0, v125
	v_add_f32_e32 v121, 1.0, v121
	v_add_f32_e32 v126, 1.0, v126
	v_add_f32_e32 v122, 1.0, v122
	v_add_f32_e32 v123, 1.0, v123
	v_add_f32_e32 v127, 1.0, v127
	v_rcp_f32_e32 v124, v124
	v_rcp_f32_e32 v120, v120
	v_rcp_f32_e32 v121, v121
	v_rcp_f32_e32 v126, v126
	v_rcp_f32_e32 v122, v122
	v_rcp_f32_e32 v123, v123
	v_rcp_f32_e32 v127, v127
	v_rcp_f32_e32 v125, v125
	s_nop 0
	v_cvt_pk_f16_f32 v123, v122, v123
	v_cvt_pk_f16_f32 v122, v120, v121
	v_cvt_pk_f16_f32 v121, v126, v127
	v_cvt_pk_f16_f32 v120, v124, v125
	global_store_dwordx4 v156, v[120:123], s[4:5] sc1 nt
	v_mul_f32_e32 v116, 0xbfb8aa3b, v116
	v_mul_f32_e32 v112, 0xbfb8aa3b, v112
	v_mul_f32_e32 v117, 0xbfb8aa3b, v117
	v_mul_f32_e32 v113, 0xbfb8aa3b, v113
	v_mul_f32_e32 v118, 0xbfb8aa3b, v118
	v_mul_f32_e32 v114, 0xbfb8aa3b, v114
	v_mul_f32_e32 v115, 0xbfb8aa3b, v115
	v_mul_f32_e32 v119, 0xbfb8aa3b, v119
	v_exp_f32_e32 v116, v116
	v_exp_f32_e32 v112, v112
	v_exp_f32_e32 v117, v117
	v_exp_f32_e32 v113, v113
	v_exp_f32_e32 v118, v118
	v_exp_f32_e32 v114, v114
	v_exp_f32_e32 v115, v115
	v_exp_f32_e32 v119, v119
	v_add_f32_e32 v116, 1.0, v116
	v_add_f32_e32 v112, 1.0, v112
	v_add_f32_e32 v117, 1.0, v117
	v_add_f32_e32 v113, 1.0, v113
	v_add_f32_e32 v118, 1.0, v118
	v_add_f32_e32 v114, 1.0, v114
	v_add_f32_e32 v115, 1.0, v115
	v_add_f32_e32 v119, 1.0, v119
	v_rcp_f32_e32 v116, v116
	v_rcp_f32_e32 v112, v112
	v_rcp_f32_e32 v113, v113
	v_rcp_f32_e32 v118, v118
	v_rcp_f32_e32 v114, v114
	v_rcp_f32_e32 v115, v115
	v_rcp_f32_e32 v119, v119
	v_rcp_f32_e32 v117, v117
	s_nop 0
	v_cvt_pk_f16_f32 v115, v114, v115
	v_cvt_pk_f16_f32 v114, v112, v113
	v_cvt_pk_f16_f32 v113, v118, v119
	v_cvt_pk_f16_f32 v112, v116, v117
	global_store_dwordx4 v156, v[112:115], s[4:5] offset:256 sc1 nt
	v_mul_f32_e32 v108, 0xbfb8aa3b, v108
	v_mul_f32_e32 v104, 0xbfb8aa3b, v104
	v_mul_f32_e32 v109, 0xbfb8aa3b, v109
	v_mul_f32_e32 v105, 0xbfb8aa3b, v105
	v_mul_f32_e32 v110, 0xbfb8aa3b, v110
	v_mul_f32_e32 v106, 0xbfb8aa3b, v106
	v_mul_f32_e32 v107, 0xbfb8aa3b, v107
	v_mul_f32_e32 v111, 0xbfb8aa3b, v111
	v_exp_f32_e32 v108, v108
	v_exp_f32_e32 v104, v104
	v_exp_f32_e32 v109, v109
	v_exp_f32_e32 v105, v105
	v_exp_f32_e32 v110, v110
	v_exp_f32_e32 v106, v106
	v_exp_f32_e32 v107, v107
	v_exp_f32_e32 v111, v111
	v_add_f32_e32 v108, 1.0, v108
	v_add_f32_e32 v104, 1.0, v104
	v_add_f32_e32 v109, 1.0, v109
	v_add_f32_e32 v105, 1.0, v105
	v_add_f32_e32 v110, 1.0, v110
	v_add_f32_e32 v106, 1.0, v106
	v_add_f32_e32 v107, 1.0, v107
	v_add_f32_e32 v111, 1.0, v111
	v_rcp_f32_e32 v108, v108
	v_rcp_f32_e32 v104, v104
	v_rcp_f32_e32 v105, v105
	v_rcp_f32_e32 v110, v110
	v_rcp_f32_e32 v106, v106
	v_rcp_f32_e32 v107, v107
	v_rcp_f32_e32 v111, v111
	v_rcp_f32_e32 v109, v109
	s_nop 0
	v_cvt_pk_f16_f32 v107, v106, v107
	v_cvt_pk_f16_f32 v106, v104, v105
	v_cvt_pk_f16_f32 v105, v110, v111
	v_cvt_pk_f16_f32 v104, v108, v109
	global_store_dwordx4 v157, v[104:107], s[4:5] sc1 nt
	v_mul_f32_e32 v100, 0xbfb8aa3b, v100
	v_mul_f32_e32 v96, 0xbfb8aa3b, v96
	v_mul_f32_e32 v101, 0xbfb8aa3b, v101
	v_mul_f32_e32 v97, 0xbfb8aa3b, v97
	v_mul_f32_e32 v102, 0xbfb8aa3b, v102
	v_mul_f32_e32 v98, 0xbfb8aa3b, v98
	v_mul_f32_e32 v99, 0xbfb8aa3b, v99
	v_mul_f32_e32 v103, 0xbfb8aa3b, v103
	v_exp_f32_e32 v100, v100
	v_exp_f32_e32 v96, v96
	v_exp_f32_e32 v101, v101
	v_exp_f32_e32 v97, v97
	v_exp_f32_e32 v102, v102
	v_exp_f32_e32 v98, v98
	v_exp_f32_e32 v99, v99
	v_exp_f32_e32 v103, v103
	v_add_f32_e32 v100, 1.0, v100
	v_add_f32_e32 v96, 1.0, v96
	v_add_f32_e32 v101, 1.0, v101
	v_add_f32_e32 v97, 1.0, v97
	v_add_f32_e32 v102, 1.0, v102
	v_add_f32_e32 v98, 1.0, v98
	v_add_f32_e32 v99, 1.0, v99
	v_add_f32_e32 v103, 1.0, v103
	v_rcp_f32_e32 v100, v100
	v_rcp_f32_e32 v96, v96
	v_rcp_f32_e32 v97, v97
	v_rcp_f32_e32 v102, v102
	v_rcp_f32_e32 v98, v98
	v_rcp_f32_e32 v99, v99
	v_rcp_f32_e32 v103, v103
	v_rcp_f32_e32 v101, v101
	s_nop 0
	v_cvt_pk_f16_f32 v99, v98, v99
	v_cvt_pk_f16_f32 v98, v96, v97
	v_cvt_pk_f16_f32 v97, v102, v103
	v_cvt_pk_f16_f32 v96, v100, v101
	global_store_dwordx4 v157, v[96:99], s[4:5] offset:256 sc1 nt
	v_mul_f32_e32 v92, 0xbfb8aa3b, v92
	v_mul_f32_e32 v88, 0xbfb8aa3b, v88
	v_mul_f32_e32 v93, 0xbfb8aa3b, v93
	v_mul_f32_e32 v89, 0xbfb8aa3b, v89
	v_mul_f32_e32 v94, 0xbfb8aa3b, v94
	v_mul_f32_e32 v90, 0xbfb8aa3b, v90
	v_mul_f32_e32 v91, 0xbfb8aa3b, v91
	v_mul_f32_e32 v95, 0xbfb8aa3b, v95
	v_exp_f32_e32 v92, v92
	v_exp_f32_e32 v88, v88
	v_exp_f32_e32 v93, v93
	v_exp_f32_e32 v89, v89
	v_exp_f32_e32 v94, v94
	v_exp_f32_e32 v90, v90
	v_exp_f32_e32 v91, v91
	v_exp_f32_e32 v95, v95
	v_add_f32_e32 v92, 1.0, v92
	v_add_f32_e32 v88, 1.0, v88
	v_add_f32_e32 v93, 1.0, v93
	v_add_f32_e32 v89, 1.0, v89
	v_add_f32_e32 v94, 1.0, v94
	v_add_f32_e32 v90, 1.0, v90
	v_add_f32_e32 v91, 1.0, v91
	v_add_f32_e32 v95, 1.0, v95
	v_rcp_f32_e32 v92, v92
	v_rcp_f32_e32 v88, v88
	v_rcp_f32_e32 v89, v89
	v_rcp_f32_e32 v94, v94
	v_rcp_f32_e32 v90, v90
	v_rcp_f32_e32 v91, v91
	v_rcp_f32_e32 v95, v95
	v_rcp_f32_e32 v93, v93
	s_nop 0
	v_cvt_pk_f16_f32 v91, v90, v91
	v_cvt_pk_f16_f32 v90, v88, v89
	v_cvt_pk_f16_f32 v89, v94, v95
	v_cvt_pk_f16_f32 v88, v92, v93
	global_store_dwordx4 v158, v[88:91], s[4:5] sc1 nt
	v_mul_f32_e32 v84, 0xbfb8aa3b, v84
	v_mul_f32_e32 v80, 0xbfb8aa3b, v80
	v_mul_f32_e32 v85, 0xbfb8aa3b, v85
	v_mul_f32_e32 v81, 0xbfb8aa3b, v81
	v_mul_f32_e32 v86, 0xbfb8aa3b, v86
	v_mul_f32_e32 v82, 0xbfb8aa3b, v82
	v_mul_f32_e32 v83, 0xbfb8aa3b, v83
	v_mul_f32_e32 v87, 0xbfb8aa3b, v87
	v_exp_f32_e32 v84, v84
	v_exp_f32_e32 v80, v80
	v_exp_f32_e32 v85, v85
	v_exp_f32_e32 v81, v81
	v_exp_f32_e32 v86, v86
	v_exp_f32_e32 v82, v82
	v_exp_f32_e32 v83, v83
	v_exp_f32_e32 v87, v87
	v_add_f32_e32 v84, 1.0, v84
	v_add_f32_e32 v80, 1.0, v80
	v_add_f32_e32 v85, 1.0, v85
	v_add_f32_e32 v81, 1.0, v81
	v_add_f32_e32 v86, 1.0, v86
	v_add_f32_e32 v82, 1.0, v82
	v_add_f32_e32 v83, 1.0, v83
	v_add_f32_e32 v87, 1.0, v87
	v_rcp_f32_e32 v84, v84
	v_rcp_f32_e32 v80, v80
	v_rcp_f32_e32 v81, v81
	v_rcp_f32_e32 v86, v86
	v_rcp_f32_e32 v82, v82
	v_rcp_f32_e32 v83, v83
	v_rcp_f32_e32 v87, v87
	v_rcp_f32_e32 v85, v85
	s_nop 0
	v_cvt_pk_f16_f32 v83, v82, v83
	v_cvt_pk_f16_f32 v82, v80, v81
	v_cvt_pk_f16_f32 v81, v86, v87
	v_cvt_pk_f16_f32 v80, v84, v85
	global_store_dwordx4 v158, v[80:83], s[4:5] offset:256 sc1 nt
	v_mul_f32_e32 v76, 0xbfb8aa3b, v76
	v_mul_f32_e32 v72, 0xbfb8aa3b, v72
	v_mul_f32_e32 v77, 0xbfb8aa3b, v77
	v_mul_f32_e32 v73, 0xbfb8aa3b, v73
	v_mul_f32_e32 v78, 0xbfb8aa3b, v78
	v_mul_f32_e32 v74, 0xbfb8aa3b, v74
	v_mul_f32_e32 v75, 0xbfb8aa3b, v75
	v_mul_f32_e32 v79, 0xbfb8aa3b, v79
	v_exp_f32_e32 v76, v76
	v_exp_f32_e32 v72, v72
	v_exp_f32_e32 v77, v77
	v_exp_f32_e32 v73, v73
	v_exp_f32_e32 v78, v78
	v_exp_f32_e32 v74, v74
	v_exp_f32_e32 v75, v75
	v_exp_f32_e32 v79, v79
	v_add_f32_e32 v76, 1.0, v76
	v_add_f32_e32 v72, 1.0, v72
	v_add_f32_e32 v77, 1.0, v77
	v_add_f32_e32 v73, 1.0, v73
	v_add_f32_e32 v78, 1.0, v78
	v_add_f32_e32 v74, 1.0, v74
	v_add_f32_e32 v75, 1.0, v75
	v_add_f32_e32 v79, 1.0, v79
	v_rcp_f32_e32 v76, v76
	v_rcp_f32_e32 v72, v72
	v_rcp_f32_e32 v73, v73
	v_rcp_f32_e32 v78, v78
	v_rcp_f32_e32 v74, v74
	v_rcp_f32_e32 v75, v75
	v_rcp_f32_e32 v79, v79
	v_rcp_f32_e32 v77, v77
	s_nop 0
	v_cvt_pk_f16_f32 v75, v74, v75
	v_cvt_pk_f16_f32 v74, v72, v73
	v_cvt_pk_f16_f32 v73, v78, v79
	v_cvt_pk_f16_f32 v72, v76, v77
	global_store_dwordx4 v159, v[72:75], s[4:5] sc1 nt
	v_mul_f32_e32 v68, 0xbfb8aa3b, v68
	v_mul_f32_e32 v64, 0xbfb8aa3b, v64
	v_mul_f32_e32 v69, 0xbfb8aa3b, v69
	v_mul_f32_e32 v65, 0xbfb8aa3b, v65
	v_mul_f32_e32 v70, 0xbfb8aa3b, v70
	v_mul_f32_e32 v66, 0xbfb8aa3b, v66
	v_mul_f32_e32 v67, 0xbfb8aa3b, v67
	v_mul_f32_e32 v71, 0xbfb8aa3b, v71
	v_exp_f32_e32 v68, v68
	v_exp_f32_e32 v64, v64
	v_exp_f32_e32 v69, v69
	v_exp_f32_e32 v65, v65
	v_exp_f32_e32 v70, v70
	v_exp_f32_e32 v66, v66
	v_exp_f32_e32 v67, v67
	v_exp_f32_e32 v71, v71
	v_add_f32_e32 v68, 1.0, v68
	v_add_f32_e32 v64, 1.0, v64
	v_add_f32_e32 v69, 1.0, v69
	v_add_f32_e32 v65, 1.0, v65
	v_add_f32_e32 v70, 1.0, v70
	v_add_f32_e32 v66, 1.0, v66
	v_add_f32_e32 v67, 1.0, v67
	v_add_f32_e32 v71, 1.0, v71
	v_rcp_f32_e32 v68, v68
	v_rcp_f32_e32 v64, v64
	v_rcp_f32_e32 v65, v65
	v_rcp_f32_e32 v70, v70
	v_rcp_f32_e32 v66, v66
	v_rcp_f32_e32 v67, v67
	v_rcp_f32_e32 v71, v71
	v_rcp_f32_e32 v69, v69
	s_nop 0
	v_cvt_pk_f16_f32 v67, v66, v67
	v_cvt_pk_f16_f32 v66, v64, v65
	v_cvt_pk_f16_f32 v65, v70, v71
	v_cvt_pk_f16_f32 v64, v68, v69
	global_store_dwordx4 v159, v[64:67], s[4:5] offset:256 sc1 nt
	v_mul_f32_e32 v60, 0xbfb8aa3b, v60
	v_mul_f32_e32 v56, 0xbfb8aa3b, v56
	v_mul_f32_e32 v61, 0xbfb8aa3b, v61
	v_mul_f32_e32 v57, 0xbfb8aa3b, v57
	v_mul_f32_e32 v62, 0xbfb8aa3b, v62
	v_mul_f32_e32 v58, 0xbfb8aa3b, v58
	v_mul_f32_e32 v59, 0xbfb8aa3b, v59
	v_mul_f32_e32 v63, 0xbfb8aa3b, v63
	v_exp_f32_e32 v60, v60
	v_exp_f32_e32 v56, v56
	v_exp_f32_e32 v61, v61
	v_exp_f32_e32 v57, v57
	v_exp_f32_e32 v62, v62
	v_exp_f32_e32 v58, v58
	v_exp_f32_e32 v59, v59
	v_exp_f32_e32 v63, v63
	v_add_f32_e32 v60, 1.0, v60
	v_add_f32_e32 v56, 1.0, v56
	v_add_f32_e32 v61, 1.0, v61
	v_add_f32_e32 v57, 1.0, v57
	v_add_f32_e32 v62, 1.0, v62
	v_add_f32_e32 v58, 1.0, v58
	v_add_f32_e32 v59, 1.0, v59
	v_add_f32_e32 v63, 1.0, v63
	v_rcp_f32_e32 v60, v60
	v_rcp_f32_e32 v56, v56
	v_rcp_f32_e32 v57, v57
	v_rcp_f32_e32 v62, v62
	v_rcp_f32_e32 v58, v58
	v_rcp_f32_e32 v59, v59
	v_rcp_f32_e32 v63, v63
	v_rcp_f32_e32 v61, v61
	s_nop 0
	v_cvt_pk_f16_f32 v59, v58, v59
	v_cvt_pk_f16_f32 v58, v56, v57
	v_cvt_pk_f16_f32 v57, v62, v63
	v_cvt_pk_f16_f32 v56, v60, v61
	global_store_dwordx4 v160, v[56:59], s[4:5] sc1 nt
	v_mul_f32_e32 v52, 0xbfb8aa3b, v52
	v_mul_f32_e32 v48, 0xbfb8aa3b, v48
	v_mul_f32_e32 v53, 0xbfb8aa3b, v53
	v_mul_f32_e32 v49, 0xbfb8aa3b, v49
	v_mul_f32_e32 v54, 0xbfb8aa3b, v54
	v_mul_f32_e32 v50, 0xbfb8aa3b, v50
	v_mul_f32_e32 v51, 0xbfb8aa3b, v51
	v_mul_f32_e32 v55, 0xbfb8aa3b, v55
	v_exp_f32_e32 v52, v52
	v_exp_f32_e32 v48, v48
	v_exp_f32_e32 v53, v53
	v_exp_f32_e32 v49, v49
	v_exp_f32_e32 v54, v54
	v_exp_f32_e32 v50, v50
	v_exp_f32_e32 v51, v51
	v_exp_f32_e32 v55, v55
	v_add_f32_e32 v52, 1.0, v52
	v_add_f32_e32 v48, 1.0, v48
	v_add_f32_e32 v53, 1.0, v53
	v_add_f32_e32 v49, 1.0, v49
	v_add_f32_e32 v54, 1.0, v54
	v_add_f32_e32 v50, 1.0, v50
	v_add_f32_e32 v51, 1.0, v51
	v_add_f32_e32 v55, 1.0, v55
	v_rcp_f32_e32 v52, v52
	v_rcp_f32_e32 v48, v48
	v_rcp_f32_e32 v49, v49
	v_rcp_f32_e32 v54, v54
	v_rcp_f32_e32 v50, v50
	v_rcp_f32_e32 v51, v51
	v_rcp_f32_e32 v55, v55
	v_rcp_f32_e32 v53, v53
	s_nop 0
	v_cvt_pk_f16_f32 v51, v50, v51
	v_cvt_pk_f16_f32 v50, v48, v49
	v_cvt_pk_f16_f32 v49, v54, v55
	v_cvt_pk_f16_f32 v48, v52, v53
	global_store_dwordx4 v160, v[48:51], s[4:5] offset:256 sc1 nt
	v_mul_f32_e32 v44, 0xbfb8aa3b, v44
	v_mul_f32_e32 v40, 0xbfb8aa3b, v40
	v_mul_f32_e32 v45, 0xbfb8aa3b, v45
	v_mul_f32_e32 v41, 0xbfb8aa3b, v41
	v_mul_f32_e32 v46, 0xbfb8aa3b, v46
	v_mul_f32_e32 v42, 0xbfb8aa3b, v42
	v_mul_f32_e32 v43, 0xbfb8aa3b, v43
	v_mul_f32_e32 v47, 0xbfb8aa3b, v47
	v_exp_f32_e32 v44, v44
	v_exp_f32_e32 v40, v40
	v_exp_f32_e32 v45, v45
	v_exp_f32_e32 v41, v41
	v_exp_f32_e32 v46, v46
	v_exp_f32_e32 v42, v42
	v_exp_f32_e32 v43, v43
	v_exp_f32_e32 v47, v47
	v_add_f32_e32 v44, 1.0, v44
	v_add_f32_e32 v40, 1.0, v40
	v_add_f32_e32 v45, 1.0, v45
	v_add_f32_e32 v41, 1.0, v41
	v_add_f32_e32 v46, 1.0, v46
	v_add_f32_e32 v42, 1.0, v42
	v_add_f32_e32 v43, 1.0, v43
	v_add_f32_e32 v47, 1.0, v47
	v_rcp_f32_e32 v44, v44
	v_rcp_f32_e32 v40, v40
	v_rcp_f32_e32 v41, v41
	v_rcp_f32_e32 v46, v46
	v_rcp_f32_e32 v42, v42
	v_rcp_f32_e32 v43, v43
	v_rcp_f32_e32 v47, v47
	v_rcp_f32_e32 v45, v45
	s_nop 0
	v_cvt_pk_f16_f32 v43, v42, v43
	v_cvt_pk_f16_f32 v42, v40, v41
	v_cvt_pk_f16_f32 v41, v46, v47
	v_cvt_pk_f16_f32 v40, v44, v45
	global_store_dwordx4 v161, v[40:43], s[4:5] sc1 nt
	v_mul_f32_e32 v36, 0xbfb8aa3b, v36
	v_mul_f32_e32 v32, 0xbfb8aa3b, v32
	v_mul_f32_e32 v37, 0xbfb8aa3b, v37
	v_mul_f32_e32 v33, 0xbfb8aa3b, v33
	v_mul_f32_e32 v38, 0xbfb8aa3b, v38
	v_mul_f32_e32 v34, 0xbfb8aa3b, v34
	v_mul_f32_e32 v35, 0xbfb8aa3b, v35
	v_mul_f32_e32 v39, 0xbfb8aa3b, v39
	v_exp_f32_e32 v36, v36
	v_exp_f32_e32 v32, v32
	v_exp_f32_e32 v37, v37
	v_exp_f32_e32 v33, v33
	v_exp_f32_e32 v38, v38
	v_exp_f32_e32 v34, v34
	v_exp_f32_e32 v35, v35
	v_exp_f32_e32 v39, v39
	v_add_f32_e32 v36, 1.0, v36
	v_add_f32_e32 v32, 1.0, v32
	v_add_f32_e32 v37, 1.0, v37
	v_add_f32_e32 v33, 1.0, v33
	v_add_f32_e32 v38, 1.0, v38
	v_add_f32_e32 v34, 1.0, v34
	v_add_f32_e32 v35, 1.0, v35
	v_add_f32_e32 v39, 1.0, v39
	v_rcp_f32_e32 v36, v36
	v_rcp_f32_e32 v32, v32
	v_rcp_f32_e32 v33, v33
	v_rcp_f32_e32 v38, v38
	v_rcp_f32_e32 v34, v34
	v_rcp_f32_e32 v35, v35
	v_rcp_f32_e32 v39, v39
	v_rcp_f32_e32 v37, v37
	s_nop 0
	v_cvt_pk_f16_f32 v35, v34, v35
	v_cvt_pk_f16_f32 v34, v32, v33
	v_cvt_pk_f16_f32 v33, v38, v39
	v_cvt_pk_f16_f32 v32, v36, v37
	global_store_dwordx4 v161, v[32:35], s[4:5] offset:256 sc1 nt
	v_mul_f32_e32 v28, 0xbfb8aa3b, v28
	v_mul_f32_e32 v24, 0xbfb8aa3b, v24
	v_mul_f32_e32 v29, 0xbfb8aa3b, v29
	v_mul_f32_e32 v25, 0xbfb8aa3b, v25
	v_mul_f32_e32 v30, 0xbfb8aa3b, v30
	v_mul_f32_e32 v26, 0xbfb8aa3b, v26
	v_mul_f32_e32 v27, 0xbfb8aa3b, v27
	v_mul_f32_e32 v31, 0xbfb8aa3b, v31
	v_exp_f32_e32 v28, v28
	v_exp_f32_e32 v24, v24
	v_exp_f32_e32 v29, v29
	v_exp_f32_e32 v25, v25
	v_exp_f32_e32 v30, v30
	v_exp_f32_e32 v26, v26
	v_exp_f32_e32 v27, v27
	v_exp_f32_e32 v31, v31
	v_add_f32_e32 v28, 1.0, v28
	v_add_f32_e32 v24, 1.0, v24
	v_add_f32_e32 v29, 1.0, v29
	v_add_f32_e32 v25, 1.0, v25
	v_add_f32_e32 v30, 1.0, v30
	v_add_f32_e32 v26, 1.0, v26
	v_add_f32_e32 v27, 1.0, v27
	v_add_f32_e32 v31, 1.0, v31
	v_rcp_f32_e32 v28, v28
	v_rcp_f32_e32 v24, v24
	v_rcp_f32_e32 v25, v25
	v_rcp_f32_e32 v30, v30
	v_rcp_f32_e32 v26, v26
	v_rcp_f32_e32 v27, v27
	v_rcp_f32_e32 v31, v31
	v_rcp_f32_e32 v29, v29
	s_nop 0
	v_cvt_pk_f16_f32 v27, v26, v27
	v_cvt_pk_f16_f32 v26, v24, v25
	v_cvt_pk_f16_f32 v25, v30, v31
	v_cvt_pk_f16_f32 v24, v28, v29
	global_store_dwordx4 v162, v[24:27], s[4:5] sc1 nt
	v_mul_f32_e32 v20, 0xbfb8aa3b, v20
	v_mul_f32_e32 v16, 0xbfb8aa3b, v16
	v_mul_f32_e32 v21, 0xbfb8aa3b, v21
	v_mul_f32_e32 v17, 0xbfb8aa3b, v17
	v_mul_f32_e32 v22, 0xbfb8aa3b, v22
	v_mul_f32_e32 v18, 0xbfb8aa3b, v18
	v_mul_f32_e32 v19, 0xbfb8aa3b, v19
	v_mul_f32_e32 v23, 0xbfb8aa3b, v23
	v_exp_f32_e32 v20, v20
	v_exp_f32_e32 v16, v16
	v_exp_f32_e32 v21, v21
	v_exp_f32_e32 v17, v17
	v_exp_f32_e32 v22, v22
	v_exp_f32_e32 v18, v18
	v_exp_f32_e32 v19, v19
	v_exp_f32_e32 v23, v23
	v_add_f32_e32 v20, 1.0, v20
	v_add_f32_e32 v16, 1.0, v16
	v_add_f32_e32 v21, 1.0, v21
	v_add_f32_e32 v17, 1.0, v17
	v_add_f32_e32 v22, 1.0, v22
	v_add_f32_e32 v18, 1.0, v18
	v_add_f32_e32 v19, 1.0, v19
	v_add_f32_e32 v23, 1.0, v23
	v_rcp_f32_e32 v20, v20
	v_rcp_f32_e32 v16, v16
	v_rcp_f32_e32 v17, v17
	v_rcp_f32_e32 v22, v22
	v_rcp_f32_e32 v18, v18
	v_rcp_f32_e32 v19, v19
	v_rcp_f32_e32 v23, v23
	v_rcp_f32_e32 v21, v21
	s_nop 0
	v_cvt_pk_f16_f32 v19, v18, v19
	v_cvt_pk_f16_f32 v18, v16, v17
	v_cvt_pk_f16_f32 v17, v22, v23
	v_cvt_pk_f16_f32 v16, v20, v21
	global_store_dwordx4 v162, v[16:19], s[4:5] offset:256 sc1 nt
	v_mul_f32_e32 v12, 0xbfb8aa3b, v12
	v_mul_f32_e32 v8, 0xbfb8aa3b, v8
	v_mul_f32_e32 v13, 0xbfb8aa3b, v13
	v_mul_f32_e32 v9, 0xbfb8aa3b, v9
	v_mul_f32_e32 v14, 0xbfb8aa3b, v14
	v_mul_f32_e32 v10, 0xbfb8aa3b, v10
	v_mul_f32_e32 v11, 0xbfb8aa3b, v11
	v_mul_f32_e32 v15, 0xbfb8aa3b, v15
	v_exp_f32_e32 v12, v12
	v_exp_f32_e32 v8, v8
	v_exp_f32_e32 v13, v13
	v_exp_f32_e32 v9, v9
	v_exp_f32_e32 v14, v14
	v_exp_f32_e32 v10, v10
	v_exp_f32_e32 v11, v11
	v_exp_f32_e32 v15, v15
	v_add_f32_e32 v12, 1.0, v12
	v_add_f32_e32 v8, 1.0, v8
	v_add_f32_e32 v13, 1.0, v13
	v_add_f32_e32 v9, 1.0, v9
	v_add_f32_e32 v14, 1.0, v14
	v_add_f32_e32 v10, 1.0, v10
	v_add_f32_e32 v11, 1.0, v11
	v_add_f32_e32 v15, 1.0, v15
	v_rcp_f32_e32 v12, v12
	v_rcp_f32_e32 v8, v8
	v_rcp_f32_e32 v9, v9
	v_rcp_f32_e32 v14, v14
	v_rcp_f32_e32 v10, v10
	v_rcp_f32_e32 v11, v11
	v_rcp_f32_e32 v15, v15
	v_rcp_f32_e32 v13, v13
	s_nop 0
	v_cvt_pk_f16_f32 v11, v10, v11
	v_cvt_pk_f16_f32 v10, v8, v9
	v_cvt_pk_f16_f32 v9, v14, v15
	v_cvt_pk_f16_f32 v8, v12, v13
	global_store_dwordx4 v163, v[8:11], s[4:5] sc1 nt
	v_mul_f32_e32 v4, 0xbfb8aa3b, v4
	v_mul_f32_e32 v0, 0xbfb8aa3b, v0
	v_mul_f32_e32 v5, 0xbfb8aa3b, v5
	v_mul_f32_e32 v1, 0xbfb8aa3b, v1
	v_mul_f32_e32 v6, 0xbfb8aa3b, v6
	v_mul_f32_e32 v2, 0xbfb8aa3b, v2
	v_mul_f32_e32 v3, 0xbfb8aa3b, v3
	v_mul_f32_e32 v7, 0xbfb8aa3b, v7
	v_exp_f32_e32 v4, v4
	v_exp_f32_e32 v0, v0
	v_exp_f32_e32 v5, v5
	v_exp_f32_e32 v1, v1
	v_exp_f32_e32 v6, v6
	v_exp_f32_e32 v2, v2
	v_exp_f32_e32 v3, v3
	v_exp_f32_e32 v7, v7
	v_add_f32_e32 v4, 1.0, v4
	v_add_f32_e32 v0, 1.0, v0
	v_add_f32_e32 v5, 1.0, v5
	v_add_f32_e32 v1, 1.0, v1
	v_add_f32_e32 v6, 1.0, v6
	v_add_f32_e32 v2, 1.0, v2
	v_add_f32_e32 v3, 1.0, v3
	v_add_f32_e32 v7, 1.0, v7
	v_rcp_f32_e32 v4, v4
	v_rcp_f32_e32 v0, v0
	v_rcp_f32_e32 v1, v1
	v_rcp_f32_e32 v6, v6
	v_rcp_f32_e32 v2, v2
	v_rcp_f32_e32 v3, v3
	v_rcp_f32_e32 v7, v7
	v_rcp_f32_e32 v5, v5
	s_nop 0
	v_cvt_pk_f16_f32 v3, v2, v3
	v_cvt_pk_f16_f32 v2, v0, v1
	v_cvt_pk_f16_f32 v1, v6, v7
	v_cvt_pk_f16_f32 v0, v4, v5
	global_store_dwordx4 v163, v[0:3], s[4:5] offset:256 sc1 nt
	s_branch .LBB0_1145
.Lsh_k3:
	v_mov_b32_e32 v156, v136
	v_add_u32_e32 v157, 0x8000, v136
	v_add_u32_e32 v158, 0x10000, v136
	v_add_u32_e32 v159, 0x18000, v136
	v_add_u32_e32 v160, 0x40000, v136
	v_add_u32_e32 v161, 0x48000, v136
	v_add_u32_e32 v162, 0x50000, v136
	v_add_u32_e32 v163, 0x58000, v136
	global_load_dwordx4 v[164:167], v156, s[44:45]
	global_load_dwordx4 v[168:171], v156, s[44:45] offset:256
	global_load_dwordx4 v[172:175], v157, s[44:45]
	global_load_dwordx4 v[176:179], v157, s[44:45] offset:256
	global_load_dwordx4 v[180:183], v158, s[44:45]
	global_load_dwordx4 v[184:187], v158, s[44:45] offset:256
	global_load_dwordx4 v[188:191], v159, s[44:45]
	global_load_dwordx4 v[192:195], v159, s[44:45] offset:256
	s_waitcnt vmcnt(7)
	v_cvt_f32_f16_e32 v196, v164
	v_cvt_f32_f16_sdwa v197, v164 dst_sel:DWORD dst_unused:UNUSED_PAD src0_sel:WORD_1
	v_cvt_f32_f16_e32 v198, v165
	v_cvt_f32_f16_sdwa v199, v165 dst_sel:DWORD dst_unused:UNUSED_PAD src0_sel:WORD_1
	v_cvt_f32_f16_e32 v200, v166
	v_cvt_f32_f16_sdwa v201, v166 dst_sel:DWORD dst_unused:UNUSED_PAD src0_sel:WORD_1
	v_cvt_f32_f16_e32 v202, v167
	v_cvt_f32_f16_sdwa v203, v167 dst_sel:DWORD dst_unused:UNUSED_PAD src0_sel:WORD_1
	v_pk_mul_f32 v[124:125], v[124:125], v[196:197]
	v_pk_mul_f32 v[126:127], v[126:127], v[198:199]
	v_pk_mul_f32 v[120:121], v[120:121], v[200:201]
	v_pk_mul_f32 v[122:123], v[122:123], v[202:203]
	v_cvt_pk_f16_f32 v164, v124, v125
	v_cvt_pk_f16_f32 v165, v126, v127
	v_cvt_pk_f16_f32 v166, v120, v121
	v_cvt_pk_f16_f32 v167, v122, v123
	global_store_dwordx4 v156, v[164:167], s[44:45] sc1 nt
	s_nop 1
	global_load_dwordx4 v[164:167], v160, s[44:45]
	s_waitcnt vmcnt(8)
	v_cvt_f32_f16_e32 v196, v168
	v_cvt_f32_f16_sdwa v197, v168 dst_sel:DWORD dst_unused:UNUSED_PAD src0_sel:WORD_1
	v_cvt_f32_f16_e32 v198, v169
	v_cvt_f32_f16_sdwa v199, v169 dst_sel:DWORD dst_unused:UNUSED_PAD src0_sel:WORD_1
	v_cvt_f32_f16_e32 v200, v170
	v_cvt_f32_f16_sdwa v201, v170 dst_sel:DWORD dst_unused:UNUSED_PAD src0_sel:WORD_1
	v_cvt_f32_f16_e32 v202, v171
	v_cvt_f32_f16_sdwa v203, v171 dst_sel:DWORD dst_unused:UNUSED_PAD src0_sel:WORD_1
	v_pk_mul_f32 v[116:117], v[116:117], v[196:197]
	v_pk_mul_f32 v[118:119], v[118:119], v[198:199]
	v_pk_mul_f32 v[112:113], v[112:113], v[200:201]
	v_pk_mul_f32 v[114:115], v[114:115], v[202:203]
	v_cvt_pk_f16_f32 v168, v116, v117
	v_cvt_pk_f16_f32 v169, v118, v119
	v_cvt_pk_f16_f32 v170, v112, v113
	v_cvt_pk_f16_f32 v171, v114, v115
	global_store_dwordx4 v156, v[168:171], s[44:45] offset:256 sc1 nt
	s_nop 1
	global_load_dwordx4 v[168:171], v160, s[44:45] offset:256
	s_waitcnt vmcnt(9)
	v_cvt_f32_f16_e32 v196, v172
	v_cvt_f32_f16_sdwa v197, v172 dst_sel:DWORD dst_unused:UNUSED_PAD src0_sel:WORD_1
	v_cvt_f32_f16_e32 v198, v173
	v_cvt_f32_f16_sdwa v199, v173 dst_sel:DWORD dst_unused:UNUSED_PAD src0_sel:WORD_1
	v_cvt_f32_f16_e32 v200, v174
	v_cvt_f32_f16_sdwa v201, v174 dst_sel:DWORD dst_unused:UNUSED_PAD src0_sel:WORD_1
	v_cvt_f32_f16_e32 v202, v175
	v_cvt_f32_f16_sdwa v203, v175 dst_sel:DWORD dst_unused:UNUSED_PAD src0_sel:WORD_1
	v_pk_mul_f32 v[108:109], v[108:109], v[196:197]
	v_pk_mul_f32 v[110:111], v[110:111], v[198:199]
	v_pk_mul_f32 v[104:105], v[104:105], v[200:201]
	v_pk_mul_f32 v[106:107], v[106:107], v[202:203]
	v_cvt_pk_f16_f32 v172, v108, v109
	v_cvt_pk_f16_f32 v173, v110, v111
	v_cvt_pk_f16_f32 v174, v104, v105
	v_cvt_pk_f16_f32 v175, v106, v107
	global_store_dwordx4 v157, v[172:175], s[44:45] sc1 nt
	s_nop 1
	global_load_dwordx4 v[172:175], v161, s[44:45]
	s_waitcnt vmcnt(10)
	v_cvt_f32_f16_e32 v196, v176
	v_cvt_f32_f16_sdwa v197, v176 dst_sel:DWORD dst_unused:UNUSED_PAD src0_sel:WORD_1
	v_cvt_f32_f16_e32 v198, v177
	v_cvt_f32_f16_sdwa v199, v177 dst_sel:DWORD dst_unused:UNUSED_PAD src0_sel:WORD_1
	v_cvt_f32_f16_e32 v200, v178
	v_cvt_f32_f16_sdwa v201, v178 dst_sel:DWORD dst_unused:UNUSED_PAD src0_sel:WORD_1
	v_cvt_f32_f16_e32 v202, v179
	v_cvt_f32_f16_sdwa v203, v179 dst_sel:DWORD dst_unused:UNUSED_PAD src0_sel:WORD_1
	v_pk_mul_f32 v[100:101], v[100:101], v[196:197]
	v_pk_mul_f32 v[102:103], v[102:103], v[198:199]
	v_pk_mul_f32 v[96:97], v[96:97], v[200:201]
	v_pk_mul_f32 v[98:99], v[98:99], v[202:203]
	v_cvt_pk_f16_f32 v176, v100, v101
	v_cvt_pk_f16_f32 v177, v102, v103
	v_cvt_pk_f16_f32 v178, v96, v97
	v_cvt_pk_f16_f32 v179, v98, v99
	global_store_dwordx4 v157, v[176:179], s[44:45] offset:256 sc1 nt
	s_nop 1
	global_load_dwordx4 v[176:179], v161, s[44:45] offset:256
	s_waitcnt vmcnt(11)
	v_cvt_f32_f16_e32 v196, v180
	v_cvt_f32_f16_sdwa v197, v180 dst_sel:DWORD dst_unused:UNUSED_PAD src0_sel:WORD_1
	v_cvt_f32_f16_e32 v198, v181
	v_cvt_f32_f16_sdwa v199, v181 dst_sel:DWORD dst_unused:UNUSED_PAD src0_sel:WORD_1
	v_cvt_f32_f16_e32 v200, v182
	v_cvt_f32_f16_sdwa v201, v182 dst_sel:DWORD dst_unused:UNUSED_PAD src0_sel:WORD_1
	v_cvt_f32_f16_e32 v202, v183
	v_cvt_f32_f16_sdwa v203, v183 dst_sel:DWORD dst_unused:UNUSED_PAD src0_sel:WORD_1
	v_pk_mul_f32 v[92:93], v[92:93], v[196:197]
	v_pk_mul_f32 v[94:95], v[94:95], v[198:199]
	v_pk_mul_f32 v[88:89], v[88:89], v[200:201]
	v_pk_mul_f32 v[90:91], v[90:91], v[202:203]
	v_cvt_pk_f16_f32 v180, v92, v93
	v_cvt_pk_f16_f32 v181, v94, v95
	v_cvt_pk_f16_f32 v182, v88, v89
	v_cvt_pk_f16_f32 v183, v90, v91
	global_store_dwordx4 v158, v[180:183], s[44:45] sc1 nt
	s_nop 1
	global_load_dwordx4 v[180:183], v162, s[44:45]
	s_waitcnt vmcnt(12)
	v_cvt_f32_f16_e32 v196, v184
	v_cvt_f32_f16_sdwa v197, v184 dst_sel:DWORD dst_unused:UNUSED_PAD src0_sel:WORD_1
	v_cvt_f32_f16_e32 v198, v185
	v_cvt_f32_f16_sdwa v199, v185 dst_sel:DWORD dst_unused:UNUSED_PAD src0_sel:WORD_1
	v_cvt_f32_f16_e32 v200, v186
	v_cvt_f32_f16_sdwa v201, v186 dst_sel:DWORD dst_unused:UNUSED_PAD src0_sel:WORD_1
	v_cvt_f32_f16_e32 v202, v187
	v_cvt_f32_f16_sdwa v203, v187 dst_sel:DWORD dst_unused:UNUSED_PAD src0_sel:WORD_1
	v_pk_mul_f32 v[84:85], v[84:85], v[196:197]
	v_pk_mul_f32 v[86:87], v[86:87], v[198:199]
	v_pk_mul_f32 v[80:81], v[80:81], v[200:201]
	v_pk_mul_f32 v[82:83], v[82:83], v[202:203]
	v_cvt_pk_f16_f32 v184, v84, v85
	v_cvt_pk_f16_f32 v185, v86, v87
	v_cvt_pk_f16_f32 v186, v80, v81
	v_cvt_pk_f16_f32 v187, v82, v83
	global_store_dwordx4 v158, v[184:187], s[44:45] offset:256 sc1 nt
	s_nop 1
	global_load_dwordx4 v[184:187], v162, s[44:45] offset:256
	s_waitcnt vmcnt(13)
	v_cvt_f32_f16_e32 v196, v188
	v_cvt_f32_f16_sdwa v197, v188 dst_sel:DWORD dst_unused:UNUSED_PAD src0_sel:WORD_1
	v_cvt_f32_f16_e32 v198, v189
	v_cvt_f32_f16_sdwa v199, v189 dst_sel:DWORD dst_unused:UNUSED_PAD src0_sel:WORD_1
	v_cvt_f32_f16_e32 v200, v190
	v_cvt_f32_f16_sdwa v201, v190 dst_sel:DWORD dst_unused:UNUSED_PAD src0_sel:WORD_1
	v_cvt_f32_f16_e32 v202, v191
	v_cvt_f32_f16_sdwa v203, v191 dst_sel:DWORD dst_unused:UNUSED_PAD src0_sel:WORD_1
	v_pk_mul_f32 v[76:77], v[76:77], v[196:197]
	v_pk_mul_f32 v[78:79], v[78:79], v[198:199]
	v_pk_mul_f32 v[72:73], v[72:73], v[200:201]
	v_pk_mul_f32 v[74:75], v[74:75], v[202:203]
	v_cvt_pk_f16_f32 v188, v76, v77
	v_cvt_pk_f16_f32 v189, v78, v79
	v_cvt_pk_f16_f32 v190, v72, v73
	v_cvt_pk_f16_f32 v191, v74, v75
	global_store_dwordx4 v159, v[188:191], s[44:45] sc1 nt
	s_nop 1
	global_load_dwordx4 v[188:191], v163, s[44:45]
	s_waitcnt vmcnt(14)
	v_cvt_f32_f16_e32 v196, v192
	v_cvt_f32_f16_sdwa v197, v192 dst_sel:DWORD dst_unused:UNUSED_PAD src0_sel:WORD_1
	v_cvt_f32_f16_e32 v198, v193
	v_cvt_f32_f16_sdwa v199, v193 dst_sel:DWORD dst_unused:UNUSED_PAD src0_sel:WORD_1
	v_cvt_f32_f16_e32 v200, v194
	v_cvt_f32_f16_sdwa v201, v194 dst_sel:DWORD dst_unused:UNUSED_PAD src0_sel:WORD_1
	v_cvt_f32_f16_e32 v202, v195
	v_cvt_f32_f16_sdwa v203, v195 dst_sel:DWORD dst_unused:UNUSED_PAD src0_sel:WORD_1
	v_pk_mul_f32 v[68:69], v[68:69], v[196:197]
	v_pk_mul_f32 v[70:71], v[70:71], v[198:199]
	v_pk_mul_f32 v[64:65], v[64:65], v[200:201]
	v_pk_mul_f32 v[66:67], v[66:67], v[202:203]
	v_cvt_pk_f16_f32 v192, v68, v69
	v_cvt_pk_f16_f32 v193, v70, v71
	v_cvt_pk_f16_f32 v194, v64, v65
	v_cvt_pk_f16_f32 v195, v66, v67
	global_store_dwordx4 v159, v[192:195], s[44:45] offset:256 sc1 nt
	s_nop 1
	global_load_dwordx4 v[192:195], v163, s[44:45] offset:256
	s_waitcnt vmcnt(14)
	v_cvt_f32_f16_e32 v196, v164
	v_cvt_f32_f16_sdwa v197, v164 dst_sel:DWORD dst_unused:UNUSED_PAD src0_sel:WORD_1
	v_cvt_f32_f16_e32 v198, v165
	v_cvt_f32_f16_sdwa v199, v165 dst_sel:DWORD dst_unused:UNUSED_PAD src0_sel:WORD_1
	v_cvt_f32_f16_e32 v200, v166
	v_cvt_f32_f16_sdwa v201, v166 dst_sel:DWORD dst_unused:UNUSED_PAD src0_sel:WORD_1
	v_cvt_f32_f16_e32 v202, v167
	v_cvt_f32_f16_sdwa v203, v167 dst_sel:DWORD dst_unused:UNUSED_PAD src0_sel:WORD_1
	v_pk_mul_f32 v[60:61], v[60:61], v[196:197]
	v_pk_mul_f32 v[62:63], v[62:63], v[198:199]
	v_pk_mul_f32 v[56:57], v[56:57], v[200:201]
	v_pk_mul_f32 v[58:59], v[58:59], v[202:203]
	v_cvt_pk_f16_f32 v164, v60, v61
	v_cvt_pk_f16_f32 v165, v62, v63
	v_cvt_pk_f16_f32 v166, v56, v57
	v_cvt_pk_f16_f32 v167, v58, v59
	global_store_dwordx4 v160, v[164:167], s[44:45] sc1 nt
	s_nop 1
	s_waitcnt vmcnt(13)
	v_cvt_f32_f16_e32 v196, v168
	v_cvt_f32_f16_sdwa v197, v168 dst_sel:DWORD dst_unused:UNUSED_PAD src0_sel:WORD_1
	v_cvt_f32_f16_e32 v198, v169
	v_cvt_f32_f16_sdwa v199, v169 dst_sel:DWORD dst_unused:UNUSED_PAD src0_sel:WORD_1
	v_cvt_f32_f16_e32 v200, v170
	v_cvt_f32_f16_sdwa v201, v170 dst_sel:DWORD dst_unused:UNUSED_PAD src0_sel:WORD_1
	v_cvt_f32_f16_e32 v202, v171
	v_cvt_f32_f16_sdwa v203, v171 dst_sel:DWORD dst_unused:UNUSED_PAD src0_sel:WORD_1
	v_pk_mul_f32 v[52:53], v[52:53], v[196:197]
	v_pk_mul_f32 v[54:55], v[54:55], v[198:199]
	v_pk_mul_f32 v[48:49], v[48:49], v[200:201]
	v_pk_mul_f32 v[50:51], v[50:51], v[202:203]
	v_cvt_pk_f16_f32 v168, v52, v53
	v_cvt_pk_f16_f32 v169, v54, v55
	v_cvt_pk_f16_f32 v170, v48, v49
	v_cvt_pk_f16_f32 v171, v50, v51
	global_store_dwordx4 v160, v[168:171], s[44:45] offset:256 sc1 nt
	s_nop 1
	s_waitcnt vmcnt(12)
	v_cvt_f32_f16_e32 v196, v172
	v_cvt_f32_f16_sdwa v197, v172 dst_sel:DWORD dst_unused:UNUSED_PAD src0_sel:WORD_1
	v_cvt_f32_f16_e32 v198, v173
	v_cvt_f32_f16_sdwa v199, v173 dst_sel:DWORD dst_unused:UNUSED_PAD src0_sel:WORD_1
	v_cvt_f32_f16_e32 v200, v174
	v_cvt_f32_f16_sdwa v201, v174 dst_sel:DWORD dst_unused:UNUSED_PAD src0_sel:WORD_1
	v_cvt_f32_f16_e32 v202, v175
	v_cvt_f32_f16_sdwa v203, v175 dst_sel:DWORD dst_unused:UNUSED_PAD src0_sel:WORD_1
	v_pk_mul_f32 v[44:45], v[44:45], v[196:197]
	v_pk_mul_f32 v[46:47], v[46:47], v[198:199]
	v_pk_mul_f32 v[40:41], v[40:41], v[200:201]
	v_pk_mul_f32 v[42:43], v[42:43], v[202:203]
	v_cvt_pk_f16_f32 v172, v44, v45
	v_cvt_pk_f16_f32 v173, v46, v47
	v_cvt_pk_f16_f32 v174, v40, v41
	v_cvt_pk_f16_f32 v175, v42, v43
	global_store_dwordx4 v161, v[172:175], s[44:45] sc1 nt
	s_nop 1
	s_waitcnt vmcnt(11)
	v_cvt_f32_f16_e32 v196, v176
	v_cvt_f32_f16_sdwa v197, v176 dst_sel:DWORD dst_unused:UNUSED_PAD src0_sel:WORD_1
	v_cvt_f32_f16_e32 v198, v177
	v_cvt_f32_f16_sdwa v199, v177 dst_sel:DWORD dst_unused:UNUSED_PAD src0_sel:WORD_1
	v_cvt_f32_f16_e32 v200, v178
	v_cvt_f32_f16_sdwa v201, v178 dst_sel:DWORD dst_unused:UNUSED_PAD src0_sel:WORD_1
	v_cvt_f32_f16_e32 v202, v179
	v_cvt_f32_f16_sdwa v203, v179 dst_sel:DWORD dst_unused:UNUSED_PAD src0_sel:WORD_1
	v_pk_mul_f32 v[36:37], v[36:37], v[196:197]
	v_pk_mul_f32 v[38:39], v[38:39], v[198:199]
	v_pk_mul_f32 v[32:33], v[32:33], v[200:201]
	v_pk_mul_f32 v[34:35], v[34:35], v[202:203]
	v_cvt_pk_f16_f32 v176, v36, v37
	v_cvt_pk_f16_f32 v177, v38, v39
	v_cvt_pk_f16_f32 v178, v32, v33
	v_cvt_pk_f16_f32 v179, v34, v35
	global_store_dwordx4 v161, v[176:179], s[44:45] offset:256 sc1 nt
	s_nop 1
	s_waitcnt vmcnt(10)
	v_cvt_f32_f16_e32 v196, v180
	v_cvt_f32_f16_sdwa v197, v180 dst_sel:DWORD dst_unused:UNUSED_PAD src0_sel:WORD_1
	v_cvt_f32_f16_e32 v198, v181
	v_cvt_f32_f16_sdwa v199, v181 dst_sel:DWORD dst_unused:UNUSED_PAD src0_sel:WORD_1
	v_cvt_f32_f16_e32 v200, v182
	v_cvt_f32_f16_sdwa v201, v182 dst_sel:DWORD dst_unused:UNUSED_PAD src0_sel:WORD_1
	v_cvt_f32_f16_e32 v202, v183
	v_cvt_f32_f16_sdwa v203, v183 dst_sel:DWORD dst_unused:UNUSED_PAD src0_sel:WORD_1
	v_pk_mul_f32 v[28:29], v[28:29], v[196:197]
	v_pk_mul_f32 v[30:31], v[30:31], v[198:199]
	v_pk_mul_f32 v[24:25], v[24:25], v[200:201]
	v_pk_mul_f32 v[26:27], v[26:27], v[202:203]
	v_cvt_pk_f16_f32 v180, v28, v29
	v_cvt_pk_f16_f32 v181, v30, v31
	v_cvt_pk_f16_f32 v182, v24, v25
	v_cvt_pk_f16_f32 v183, v26, v27
	global_store_dwordx4 v162, v[180:183], s[44:45] sc1 nt
	s_nop 1
	s_waitcnt vmcnt(9)
	v_cvt_f32_f16_e32 v196, v184
	v_cvt_f32_f16_sdwa v197, v184 dst_sel:DWORD dst_unused:UNUSED_PAD src0_sel:WORD_1
	v_cvt_f32_f16_e32 v198, v185
	v_cvt_f32_f16_sdwa v199, v185 dst_sel:DWORD dst_unused:UNUSED_PAD src0_sel:WORD_1
	v_cvt_f32_f16_e32 v200, v186
	v_cvt_f32_f16_sdwa v201, v186 dst_sel:DWORD dst_unused:UNUSED_PAD src0_sel:WORD_1
	v_cvt_f32_f16_e32 v202, v187
	v_cvt_f32_f16_sdwa v203, v187 dst_sel:DWORD dst_unused:UNUSED_PAD src0_sel:WORD_1
	v_pk_mul_f32 v[20:21], v[20:21], v[196:197]
	v_pk_mul_f32 v[22:23], v[22:23], v[198:199]
	v_pk_mul_f32 v[16:17], v[16:17], v[200:201]
	v_pk_mul_f32 v[18:19], v[18:19], v[202:203]
	v_cvt_pk_f16_f32 v184, v20, v21
	v_cvt_pk_f16_f32 v185, v22, v23
	v_cvt_pk_f16_f32 v186, v16, v17
	v_cvt_pk_f16_f32 v187, v18, v19
	global_store_dwordx4 v162, v[184:187], s[44:45] offset:256 sc1 nt
	s_nop 1
	s_waitcnt vmcnt(8)
	v_cvt_f32_f16_e32 v196, v188
	v_cvt_f32_f16_sdwa v197, v188 dst_sel:DWORD dst_unused:UNUSED_PAD src0_sel:WORD_1
	v_cvt_f32_f16_e32 v198, v189
	v_cvt_f32_f16_sdwa v199, v189 dst_sel:DWORD dst_unused:UNUSED_PAD src0_sel:WORD_1
	v_cvt_f32_f16_e32 v200, v190
	v_cvt_f32_f16_sdwa v201, v190 dst_sel:DWORD dst_unused:UNUSED_PAD src0_sel:WORD_1
	v_cvt_f32_f16_e32 v202, v191
	v_cvt_f32_f16_sdwa v203, v191 dst_sel:DWORD dst_unused:UNUSED_PAD src0_sel:WORD_1
	v_pk_mul_f32 v[12:13], v[12:13], v[196:197]
	v_pk_mul_f32 v[14:15], v[14:15], v[198:199]
	v_pk_mul_f32 v[8:9], v[8:9], v[200:201]
	v_pk_mul_f32 v[10:11], v[10:11], v[202:203]
	v_cvt_pk_f16_f32 v188, v12, v13
	v_cvt_pk_f16_f32 v189, v14, v15
	v_cvt_pk_f16_f32 v190, v8, v9
	v_cvt_pk_f16_f32 v191, v10, v11
	global_store_dwordx4 v163, v[188:191], s[44:45] sc1 nt
	s_nop 1
	s_waitcnt vmcnt(7)
	v_cvt_f32_f16_e32 v196, v192
	v_cvt_f32_f16_sdwa v197, v192 dst_sel:DWORD dst_unused:UNUSED_PAD src0_sel:WORD_1
	v_cvt_f32_f16_e32 v198, v193
	v_cvt_f32_f16_sdwa v199, v193 dst_sel:DWORD dst_unused:UNUSED_PAD src0_sel:WORD_1
	v_cvt_f32_f16_e32 v200, v194
	v_cvt_f32_f16_sdwa v201, v194 dst_sel:DWORD dst_unused:UNUSED_PAD src0_sel:WORD_1
	v_cvt_f32_f16_e32 v202, v195
	v_cvt_f32_f16_sdwa v203, v195 dst_sel:DWORD dst_unused:UNUSED_PAD src0_sel:WORD_1
	v_pk_mul_f32 v[4:5], v[4:5], v[196:197]
	v_pk_mul_f32 v[6:7], v[6:7], v[198:199]
	v_pk_mul_f32 v[0:1], v[0:1], v[200:201]
	v_pk_mul_f32 v[2:3], v[2:3], v[202:203]
	v_cvt_pk_f16_f32 v192, v4, v5
	v_cvt_pk_f16_f32 v193, v6, v7
	v_cvt_pk_f16_f32 v194, v0, v1
	v_cvt_pk_f16_f32 v195, v2, v3
	global_store_dwordx4 v163, v[192:195], s[44:45] offset:256 sc1 nt
	s_nop 1
	s_branch .LBB0_1145
